# d_out stores non-temporal (nt) in the rewritten P6' epilogue; XCD-local seams + 3us stagger; P4 epilogue rewrite
# baseline (speedup 1.0000x reference)
.Lp6_part2:
	global_load_dword v164, v253, s[16:17] sc1
	global_load_dword v165, v253, s[16:17] offset:64 sc1
	global_load_dword v166, v253, s[16:17] offset:128 sc1
	global_load_dword v167, v253, s[16:17] offset:192 sc1
	global_load_dword v168, v253, s[16:17] offset:512 sc1
	global_load_dword v169, v253, s[16:17] offset:576 sc1
	global_load_dword v170, v253, s[16:17] offset:640 sc1
	global_load_dword v171, v253, s[16:17] offset:704 sc1
	global_load_dwordx4 v[148:151], v252, s[86:87] offset:0
	global_load_dwordx4 v[152:155], v252, s[86:87] offset:16
	global_load_dwordx4 v[156:159], v252, s[86:87] offset:512
	global_load_dwordx4 v[160:163], v252, s[86:87] offset:528
	s_waitcnt vmcnt(0)
	v_fmamk_f32 v128, v164, 0x3a000000, v177
	v_mul_f32_e32 v129, 0x4f800000, v128
	v_cmp_gt_f32_e32 vcc, s9, v128
	s_nop 1
	v_cndmask_b32_e32 v128, v128, v129, vcc
	v_sqrt_f32_e32 v129, v128
	s_nop 0
	v_add_u32_e32 v130, -1, v129
	v_add_u32_e32 v131, 1, v129
	v_fma_f32 v132, -v130, v129, v128
	v_fma_f32 v133, -v131, v129, v128
	v_cmp_ge_f32_e64 s[2:3], 0, v132
	s_nop 1
	v_cndmask_b32_e64 v129, v129, v130, s[2:3]
	v_cmp_lt_f32_e64 s[2:3], 0, v133
	s_nop 1
	v_cndmask_b32_e64 v129, v129, v131, s[2:3]
	v_mul_f32_e32 v130, 0x37800000, v129
	v_cndmask_b32_e32 v129, v129, v130, vcc
	v_cmp_class_f32_e32 vcc, v128, v178
	s_nop 1
	v_cndmask_b32_e32 v128, v129, v128, vcc
	v_div_scale_f32 v129, s[2:3], v128, v128, 1.0
	v_rcp_f32_e32 v130, v129
	v_div_scale_f32 v131, vcc, 1.0, v128, 1.0
	v_fma_f32 v132, -v129, v130, 1.0
	v_fmac_f32_e32 v130, v132, v130
	v_mul_f32_e32 v132, v131, v130
	v_fma_f32 v133, -v129, v132, v131
	v_fmac_f32_e32 v132, v133, v130
	v_fma_f32 v129, -v129, v132, v131
	v_div_fmas_f32 v129, v129, v130, v132
	v_div_fixup_f32 v184, v129, v128, 1.0
	s_mov_b32 s100, s64
	s_mov_b32 s101, s65
	v_pk_mul_f32 v[188:189], v[124:125], v[184:185] op_sel_hi:[1,0]
	v_pk_mul_f32 v[190:191], v[126:127], v[184:185] op_sel_hi:[1,0]
	v_pk_mul_f32 v[192:193], v[120:121], v[184:185] op_sel_hi:[1,0]
	v_pk_mul_f32 v[194:195], v[122:123], v[184:185] op_sel_hi:[1,0]
	v_pk_mul_f32 v[188:189], v[148:149], v[188:189]
	v_pk_mul_f32 v[190:191], v[150:151], v[190:191]
	v_pk_mul_f32 v[192:193], v[152:153], v[192:193]
	v_pk_mul_f32 v[194:195], v[154:155], v[194:195]
	s_nop 0
	global_store_dwordx4 v185, v[188:191], s[100:101] offset:0 nt
	global_store_dwordx4 v185, v[192:195], s[100:101] offset:16 nt
	v_pk_mul_f32 v[196:197], v[116:117], v[184:185] op_sel_hi:[1,0]
	v_pk_mul_f32 v[198:199], v[118:119], v[184:185] op_sel_hi:[1,0]
	v_pk_mul_f32 v[200:201], v[112:113], v[184:185] op_sel_hi:[1,0]
	v_pk_mul_f32 v[202:203], v[114:115], v[184:185] op_sel_hi:[1,0]
	v_pk_mul_f32 v[196:197], v[156:157], v[196:197]
	v_pk_mul_f32 v[198:199], v[158:159], v[198:199]
	v_pk_mul_f32 v[200:201], v[160:161], v[200:201]
	v_pk_mul_f32 v[202:203], v[162:163], v[202:203]
	s_nop 0
	global_store_dwordx4 v185, v[196:199], s[100:101] offset:512 nt
	global_store_dwordx4 v185, v[200:203], s[100:101] offset:528 nt
	s_waitcnt vmcnt(14)
	v_fmamk_f32 v128, v165, 0x3a000000, v177
	v_mul_f32_e32 v129, 0x4f800000, v128
	v_cmp_gt_f32_e32 vcc, s9, v128
	s_nop 1
	v_cndmask_b32_e32 v128, v128, v129, vcc
	v_sqrt_f32_e32 v129, v128
	s_nop 0
	v_add_u32_e32 v130, -1, v129
	v_add_u32_e32 v131, 1, v129
	v_fma_f32 v132, -v130, v129, v128
	v_fma_f32 v133, -v131, v129, v128
	v_cmp_ge_f32_e64 s[2:3], 0, v132
	s_nop 1
	v_cndmask_b32_e64 v129, v129, v130, s[2:3]
	v_cmp_lt_f32_e64 s[2:3], 0, v133
	s_nop 1
	v_cndmask_b32_e64 v129, v129, v131, s[2:3]
	v_mul_f32_e32 v130, 0x37800000, v129
	v_cndmask_b32_e32 v129, v129, v130, vcc
	v_cmp_class_f32_e32 vcc, v128, v178
	s_nop 1
	v_cndmask_b32_e32 v128, v129, v128, vcc
	v_div_scale_f32 v129, s[2:3], v128, v128, 1.0
	v_rcp_f32_e32 v130, v129
	v_div_scale_f32 v131, vcc, 1.0, v128, 1.0
	v_fma_f32 v132, -v129, v130, 1.0
	v_fmac_f32_e32 v130, v132, v130
	v_mul_f32_e32 v132, v131, v130
	v_fma_f32 v133, -v129, v132, v131
	v_fmac_f32_e32 v132, v133, v130
	v_fma_f32 v129, -v129, v132, v131
	v_div_fmas_f32 v129, v129, v130, v132
	v_div_fixup_f32 v184, v129, v128, 1.0
	s_add_u32 s100, s64, 0x20000
	s_addc_u32 s101, s65, 0
	v_pk_mul_f32 v[204:205], v[108:109], v[184:185] op_sel_hi:[1,0]
	v_pk_mul_f32 v[206:207], v[110:111], v[184:185] op_sel_hi:[1,0]
	v_pk_mul_f32 v[208:209], v[104:105], v[184:185] op_sel_hi:[1,0]
	v_pk_mul_f32 v[210:211], v[106:107], v[184:185] op_sel_hi:[1,0]
	v_pk_mul_f32 v[204:205], v[148:149], v[204:205]
	v_pk_mul_f32 v[206:207], v[150:151], v[206:207]
	v_pk_mul_f32 v[208:209], v[152:153], v[208:209]
	v_pk_mul_f32 v[210:211], v[154:155], v[210:211]
	s_nop 0
	global_store_dwordx4 v185, v[204:207], s[100:101] offset:0 nt
	global_store_dwordx4 v185, v[208:211], s[100:101] offset:16 nt
	v_pk_mul_f32 v[212:213], v[100:101], v[184:185] op_sel_hi:[1,0]
	v_pk_mul_f32 v[214:215], v[102:103], v[184:185] op_sel_hi:[1,0]
	v_pk_mul_f32 v[216:217], v[96:97], v[184:185] op_sel_hi:[1,0]
	v_pk_mul_f32 v[218:219], v[98:99], v[184:185] op_sel_hi:[1,0]
	v_pk_mul_f32 v[212:213], v[156:157], v[212:213]
	v_pk_mul_f32 v[214:215], v[158:159], v[214:215]
	v_pk_mul_f32 v[216:217], v[160:161], v[216:217]
	v_pk_mul_f32 v[218:219], v[162:163], v[218:219]
	s_nop 0
	global_store_dwordx4 v185, v[212:215], s[100:101] offset:512 nt
	global_store_dwordx4 v185, v[216:219], s[100:101] offset:528 nt
	s_waitcnt vmcnt(17)
	v_fmamk_f32 v128, v166, 0x3a000000, v177
	v_mul_f32_e32 v129, 0x4f800000, v128
	v_cmp_gt_f32_e32 vcc, s9, v128
	s_nop 1
	v_cndmask_b32_e32 v128, v128, v129, vcc
	v_sqrt_f32_e32 v129, v128
	s_nop 0
	v_add_u32_e32 v130, -1, v129
	v_add_u32_e32 v131, 1, v129
	v_fma_f32 v132, -v130, v129, v128
	v_fma_f32 v133, -v131, v129, v128
	v_cmp_ge_f32_e64 s[2:3], 0, v132
	s_nop 1
	v_cndmask_b32_e64 v129, v129, v130, s[2:3]
	v_cmp_lt_f32_e64 s[2:3], 0, v133
	s_nop 1
	v_cndmask_b32_e64 v129, v129, v131, s[2:3]
	v_mul_f32_e32 v130, 0x37800000, v129
	v_cndmask_b32_e32 v129, v129, v130, vcc
	v_cmp_class_f32_e32 vcc, v128, v178
	s_nop 1
	v_cndmask_b32_e32 v128, v129, v128, vcc
	v_div_scale_f32 v129, s[2:3], v128, v128, 1.0
	v_rcp_f32_e32 v130, v129
	v_div_scale_f32 v131, vcc, 1.0, v128, 1.0
	v_fma_f32 v132, -v129, v130, 1.0
	v_fmac_f32_e32 v130, v132, v130
	v_mul_f32_e32 v132, v131, v130
	v_fma_f32 v133, -v129, v132, v131
	v_fmac_f32_e32 v132, v133, v130
	v_fma_f32 v129, -v129, v132, v131
	v_div_fmas_f32 v129, v129, v130, v132
	v_div_fixup_f32 v184, v129, v128, 1.0
	s_add_u32 s100, s64, 0x40000
	s_addc_u32 s101, s65, 0
	v_pk_mul_f32 v[220:221], v[92:93], v[184:185] op_sel_hi:[1,0]
	v_pk_mul_f32 v[222:223], v[94:95], v[184:185] op_sel_hi:[1,0]
	v_pk_mul_f32 v[224:225], v[88:89], v[184:185] op_sel_hi:[1,0]
	v_pk_mul_f32 v[226:227], v[90:91], v[184:185] op_sel_hi:[1,0]
	v_pk_mul_f32 v[220:221], v[148:149], v[220:221]
	v_pk_mul_f32 v[222:223], v[150:151], v[222:223]
	v_pk_mul_f32 v[224:225], v[152:153], v[224:225]
	v_pk_mul_f32 v[226:227], v[154:155], v[226:227]
	s_nop 0
	global_store_dwordx4 v185, v[220:223], s[100:101] offset:0 nt
	global_store_dwordx4 v185, v[224:227], s[100:101] offset:16 nt
	v_pk_mul_f32 v[228:229], v[84:85], v[184:185] op_sel_hi:[1,0]
	v_pk_mul_f32 v[230:231], v[86:87], v[184:185] op_sel_hi:[1,0]
	v_pk_mul_f32 v[232:233], v[80:81], v[184:185] op_sel_hi:[1,0]
	v_pk_mul_f32 v[234:235], v[82:83], v[184:185] op_sel_hi:[1,0]
	v_pk_mul_f32 v[228:229], v[156:157], v[228:229]
	v_pk_mul_f32 v[230:231], v[158:159], v[230:231]
	v_pk_mul_f32 v[232:233], v[160:161], v[232:233]
	v_pk_mul_f32 v[234:235], v[162:163], v[234:235]
	s_nop 0
	global_store_dwordx4 v185, v[228:231], s[100:101] offset:512 nt
	global_store_dwordx4 v185, v[232:235], s[100:101] offset:528 nt
	s_waitcnt vmcnt(20)
	v_fmamk_f32 v128, v167, 0x3a000000, v177
	v_mul_f32_e32 v129, 0x4f800000, v128
	v_cmp_gt_f32_e32 vcc, s9, v128
	s_nop 1
	v_cndmask_b32_e32 v128, v128, v129, vcc
	v_sqrt_f32_e32 v129, v128
	s_nop 0
	v_add_u32_e32 v130, -1, v129
	v_add_u32_e32 v131, 1, v129
	v_fma_f32 v132, -v130, v129, v128
	v_fma_f32 v133, -v131, v129, v128
	v_cmp_ge_f32_e64 s[2:3], 0, v132
	s_nop 1
	v_cndmask_b32_e64 v129, v129, v130, s[2:3]
	v_cmp_lt_f32_e64 s[2:3], 0, v133
	s_nop 1
	v_cndmask_b32_e64 v129, v129, v131, s[2:3]
	v_mul_f32_e32 v130, 0x37800000, v129
	v_cndmask_b32_e32 v129, v129, v130, vcc
	v_cmp_class_f32_e32 vcc, v128, v178
	s_nop 1
	v_cndmask_b32_e32 v128, v129, v128, vcc
	v_div_scale_f32 v129, s[2:3], v128, v128, 1.0
	v_rcp_f32_e32 v130, v129
	v_div_scale_f32 v131, vcc, 1.0, v128, 1.0
	v_fma_f32 v132, -v129, v130, 1.0
	v_fmac_f32_e32 v130, v132, v130
	v_mul_f32_e32 v132, v131, v130
	v_fma_f32 v133, -v129, v132, v131
	v_fmac_f32_e32 v132, v133, v130
	v_fma_f32 v129, -v129, v132, v131
	v_div_fmas_f32 v129, v129, v130, v132
	v_div_fixup_f32 v184, v129, v128, 1.0
	s_add_u32 s100, s64, 0x60000
	s_addc_u32 s101, s65, 0
	v_pk_mul_f32 v[236:237], v[76:77], v[184:185] op_sel_hi:[1,0]
	v_pk_mul_f32 v[238:239], v[78:79], v[184:185] op_sel_hi:[1,0]
	v_pk_mul_f32 v[240:241], v[72:73], v[184:185] op_sel_hi:[1,0]
	v_pk_mul_f32 v[242:243], v[74:75], v[184:185] op_sel_hi:[1,0]
	v_pk_mul_f32 v[236:237], v[148:149], v[236:237]
	v_pk_mul_f32 v[238:239], v[150:151], v[238:239]
	v_pk_mul_f32 v[240:241], v[152:153], v[240:241]
	v_pk_mul_f32 v[242:243], v[154:155], v[242:243]
	s_nop 0
	global_store_dwordx4 v185, v[236:239], s[100:101] offset:0 nt
	global_store_dwordx4 v185, v[240:243], s[100:101] offset:16 nt
	v_pk_mul_f32 v[244:245], v[68:69], v[184:185] op_sel_hi:[1,0]
	v_pk_mul_f32 v[246:247], v[70:71], v[184:185] op_sel_hi:[1,0]
	v_pk_mul_f32 v[248:249], v[64:65], v[184:185] op_sel_hi:[1,0]
	v_pk_mul_f32 v[250:251], v[66:67], v[184:185] op_sel_hi:[1,0]
	v_pk_mul_f32 v[244:245], v[156:157], v[244:245]
	v_pk_mul_f32 v[246:247], v[158:159], v[246:247]
	v_pk_mul_f32 v[248:249], v[160:161], v[248:249]
	v_pk_mul_f32 v[250:251], v[162:163], v[250:251]
	s_nop 0
	global_store_dwordx4 v185, v[244:247], s[100:101] offset:512 nt
	global_store_dwordx4 v185, v[248:251], s[100:101] offset:528 nt
	s_waitcnt vmcnt(23)
	v_fmamk_f32 v128, v168, 0x3a000000, v177
	v_mul_f32_e32 v129, 0x4f800000, v128
	v_cmp_gt_f32_e32 vcc, s9, v128
	s_nop 1
	v_cndmask_b32_e32 v128, v128, v129, vcc
	v_sqrt_f32_e32 v129, v128
	s_nop 0
	v_add_u32_e32 v130, -1, v129
	v_add_u32_e32 v131, 1, v129
	v_fma_f32 v132, -v130, v129, v128
	v_fma_f32 v133, -v131, v129, v128
	v_cmp_ge_f32_e64 s[2:3], 0, v132
	s_nop 1
	v_cndmask_b32_e64 v129, v129, v130, s[2:3]
	v_cmp_lt_f32_e64 s[2:3], 0, v133
	s_nop 1
	v_cndmask_b32_e64 v129, v129, v131, s[2:3]
	v_mul_f32_e32 v130, 0x37800000, v129
	v_cndmask_b32_e32 v129, v129, v130, vcc
	v_cmp_class_f32_e32 vcc, v128, v178
	s_nop 1
	v_cndmask_b32_e32 v128, v129, v128, vcc
	v_div_scale_f32 v129, s[2:3], v128, v128, 1.0
	v_rcp_f32_e32 v130, v129
	v_div_scale_f32 v131, vcc, 1.0, v128, 1.0
	v_fma_f32 v132, -v129, v130, 1.0
	v_fmac_f32_e32 v130, v132, v130
	v_mul_f32_e32 v132, v131, v130
	v_fma_f32 v133, -v129, v132, v131
	v_fmac_f32_e32 v132, v133, v130
	v_fma_f32 v129, -v129, v132, v131
	v_div_fmas_f32 v129, v129, v130, v132
	v_div_fixup_f32 v184, v129, v128, 1.0
	s_add_u32 s100, s64, 0x100000
	s_addc_u32 s101, s65, 0
	v_pk_mul_f32 v[188:189], v[60:61], v[184:185] op_sel_hi:[1,0]
	v_pk_mul_f32 v[190:191], v[62:63], v[184:185] op_sel_hi:[1,0]
	v_pk_mul_f32 v[192:193], v[56:57], v[184:185] op_sel_hi:[1,0]
	v_pk_mul_f32 v[194:195], v[58:59], v[184:185] op_sel_hi:[1,0]
	v_pk_mul_f32 v[188:189], v[148:149], v[188:189]
	v_pk_mul_f32 v[190:191], v[150:151], v[190:191]
	v_pk_mul_f32 v[192:193], v[152:153], v[192:193]
	v_pk_mul_f32 v[194:195], v[154:155], v[194:195]
	s_nop 0
	global_store_dwordx4 v185, v[188:191], s[100:101] offset:0 nt
	global_store_dwordx4 v185, v[192:195], s[100:101] offset:16 nt
	v_pk_mul_f32 v[196:197], v[52:53], v[184:185] op_sel_hi:[1,0]
	v_pk_mul_f32 v[198:199], v[54:55], v[184:185] op_sel_hi:[1,0]
	v_pk_mul_f32 v[200:201], v[48:49], v[184:185] op_sel_hi:[1,0]
	v_pk_mul_f32 v[202:203], v[50:51], v[184:185] op_sel_hi:[1,0]
	v_pk_mul_f32 v[196:197], v[156:157], v[196:197]
	v_pk_mul_f32 v[198:199], v[158:159], v[198:199]
	v_pk_mul_f32 v[200:201], v[160:161], v[200:201]
	v_pk_mul_f32 v[202:203], v[162:163], v[202:203]
	s_nop 0
	global_store_dwordx4 v185, v[196:199], s[100:101] offset:512 nt
	global_store_dwordx4 v185, v[200:203], s[100:101] offset:528 nt
	s_waitcnt vmcnt(26)
	v_fmamk_f32 v128, v169, 0x3a000000, v177
	v_mul_f32_e32 v129, 0x4f800000, v128
	v_cmp_gt_f32_e32 vcc, s9, v128
	s_nop 1
	v_cndmask_b32_e32 v128, v128, v129, vcc
	v_sqrt_f32_e32 v129, v128
	s_nop 0
	v_add_u32_e32 v130, -1, v129
	v_add_u32_e32 v131, 1, v129
	v_fma_f32 v132, -v130, v129, v128
	v_fma_f32 v133, -v131, v129, v128
	v_cmp_ge_f32_e64 s[2:3], 0, v132
	s_nop 1
	v_cndmask_b32_e64 v129, v129, v130, s[2:3]
	v_cmp_lt_f32_e64 s[2:3], 0, v133
	s_nop 1
	v_cndmask_b32_e64 v129, v129, v131, s[2:3]
	v_mul_f32_e32 v130, 0x37800000, v129
	v_cndmask_b32_e32 v129, v129, v130, vcc
	v_cmp_class_f32_e32 vcc, v128, v178
	s_nop 1
	v_cndmask_b32_e32 v128, v129, v128, vcc
	v_div_scale_f32 v129, s[2:3], v128, v128, 1.0
	v_rcp_f32_e32 v130, v129
	v_div_scale_f32 v131, vcc, 1.0, v128, 1.0
	v_fma_f32 v132, -v129, v130, 1.0
	v_fmac_f32_e32 v130, v132, v130
	v_mul_f32_e32 v132, v131, v130
	v_fma_f32 v133, -v129, v132, v131
	v_fmac_f32_e32 v132, v133, v130
	v_fma_f32 v129, -v129, v132, v131
	v_div_fmas_f32 v129, v129, v130, v132
	v_div_fixup_f32 v184, v129, v128, 1.0
	s_add_u32 s100, s64, 0x120000
	s_addc_u32 s101, s65, 0
	v_pk_mul_f32 v[204:205], v[44:45], v[184:185] op_sel_hi:[1,0]
	v_pk_mul_f32 v[206:207], v[46:47], v[184:185] op_sel_hi:[1,0]
	v_pk_mul_f32 v[208:209], v[40:41], v[184:185] op_sel_hi:[1,0]
	v_pk_mul_f32 v[210:211], v[42:43], v[184:185] op_sel_hi:[1,0]
	v_pk_mul_f32 v[204:205], v[148:149], v[204:205]
	v_pk_mul_f32 v[206:207], v[150:151], v[206:207]
	v_pk_mul_f32 v[208:209], v[152:153], v[208:209]
	v_pk_mul_f32 v[210:211], v[154:155], v[210:211]
	s_nop 0
	global_store_dwordx4 v185, v[204:207], s[100:101] offset:0 nt
	global_store_dwordx4 v185, v[208:211], s[100:101] offset:16 nt
	v_pk_mul_f32 v[212:213], v[36:37], v[184:185] op_sel_hi:[1,0]
	v_pk_mul_f32 v[214:215], v[38:39], v[184:185] op_sel_hi:[1,0]
	v_pk_mul_f32 v[216:217], v[32:33], v[184:185] op_sel_hi:[1,0]
	v_pk_mul_f32 v[218:219], v[34:35], v[184:185] op_sel_hi:[1,0]
	v_pk_mul_f32 v[212:213], v[156:157], v[212:213]
	v_pk_mul_f32 v[214:215], v[158:159], v[214:215]
	v_pk_mul_f32 v[216:217], v[160:161], v[216:217]
	v_pk_mul_f32 v[218:219], v[162:163], v[218:219]
	s_nop 0
	global_store_dwordx4 v185, v[212:215], s[100:101] offset:512 nt
	global_store_dwordx4 v185, v[216:219], s[100:101] offset:528 nt
	s_waitcnt vmcnt(29)
	v_fmamk_f32 v128, v170, 0x3a000000, v177
	v_mul_f32_e32 v129, 0x4f800000, v128
	v_cmp_gt_f32_e32 vcc, s9, v128
	s_nop 1
	v_cndmask_b32_e32 v128, v128, v129, vcc
	v_sqrt_f32_e32 v129, v128
	s_nop 0
	v_add_u32_e32 v130, -1, v129
	v_add_u32_e32 v131, 1, v129
	v_fma_f32 v132, -v130, v129, v128
	v_fma_f32 v133, -v131, v129, v128
	v_cmp_ge_f32_e64 s[2:3], 0, v132
	s_nop 1
	v_cndmask_b32_e64 v129, v129, v130, s[2:3]
	v_cmp_lt_f32_e64 s[2:3], 0, v133
	s_nop 1
	v_cndmask_b32_e64 v129, v129, v131, s[2:3]
	v_mul_f32_e32 v130, 0x37800000, v129
	v_cndmask_b32_e32 v129, v129, v130, vcc
	v_cmp_class_f32_e32 vcc, v128, v178
	s_nop 1
	v_cndmask_b32_e32 v128, v129, v128, vcc
	v_div_scale_f32 v129, s[2:3], v128, v128, 1.0
	v_rcp_f32_e32 v130, v129
	v_div_scale_f32 v131, vcc, 1.0, v128, 1.0
	v_fma_f32 v132, -v129, v130, 1.0
	v_fmac_f32_e32 v130, v132, v130
	v_mul_f32_e32 v132, v131, v130
	v_fma_f32 v133, -v129, v132, v131
	v_fmac_f32_e32 v132, v133, v130
	v_fma_f32 v129, -v129, v132, v131
	v_div_fmas_f32 v129, v129, v130, v132
	v_div_fixup_f32 v184, v129, v128, 1.0
	s_add_u32 s100, s64, 0x140000
	s_addc_u32 s101, s65, 0
	v_pk_mul_f32 v[220:221], v[28:29], v[184:185] op_sel_hi:[1,0]
	v_pk_mul_f32 v[222:223], v[30:31], v[184:185] op_sel_hi:[1,0]
	v_pk_mul_f32 v[224:225], v[24:25], v[184:185] op_sel_hi:[1,0]
	v_pk_mul_f32 v[226:227], v[26:27], v[184:185] op_sel_hi:[1,0]
	v_pk_mul_f32 v[220:221], v[148:149], v[220:221]
	v_pk_mul_f32 v[222:223], v[150:151], v[222:223]
	v_pk_mul_f32 v[224:225], v[152:153], v[224:225]
	v_pk_mul_f32 v[226:227], v[154:155], v[226:227]
	s_nop 0
	global_store_dwordx4 v185, v[220:223], s[100:101] offset:0 nt
	global_store_dwordx4 v185, v[224:227], s[100:101] offset:16 nt
	v_pk_mul_f32 v[228:229], v[20:21], v[184:185] op_sel_hi:[1,0]
	v_pk_mul_f32 v[230:231], v[22:23], v[184:185] op_sel_hi:[1,0]
	v_pk_mul_f32 v[232:233], v[16:17], v[184:185] op_sel_hi:[1,0]
	v_pk_mul_f32 v[234:235], v[18:19], v[184:185] op_sel_hi:[1,0]
	v_pk_mul_f32 v[228:229], v[156:157], v[228:229]
	v_pk_mul_f32 v[230:231], v[158:159], v[230:231]
	v_pk_mul_f32 v[232:233], v[160:161], v[232:233]
	v_pk_mul_f32 v[234:235], v[162:163], v[234:235]
	s_nop 0
	global_store_dwordx4 v185, v[228:231], s[100:101] offset:512 nt
	global_store_dwordx4 v185, v[232:235], s[100:101] offset:528 nt
	s_waitcnt vmcnt(32)
	v_fmamk_f32 v128, v171, 0x3a000000, v177
	v_mul_f32_e32 v129, 0x4f800000, v128
	v_cmp_gt_f32_e32 vcc, s9, v128
	s_nop 1
	v_cndmask_b32_e32 v128, v128, v129, vcc
	v_sqrt_f32_e32 v129, v128
	s_nop 0
	v_add_u32_e32 v130, -1, v129
	v_add_u32_e32 v131, 1, v129
	v_fma_f32 v132, -v130, v129, v128
	v_fma_f32 v133, -v131, v129, v128
	v_cmp_ge_f32_e64 s[2:3], 0, v132
	s_nop 1
	v_cndmask_b32_e64 v129, v129, v130, s[2:3]
	v_cmp_lt_f32_e64 s[2:3], 0, v133
	s_nop 1
	v_cndmask_b32_e64 v129, v129, v131, s[2:3]
	v_mul_f32_e32 v130, 0x37800000, v129
	v_cndmask_b32_e32 v129, v129, v130, vcc
	v_cmp_class_f32_e32 vcc, v128, v178
	s_nop 1
	v_cndmask_b32_e32 v128, v129, v128, vcc
	v_div_scale_f32 v129, s[2:3], v128, v128, 1.0
	v_rcp_f32_e32 v130, v129
	v_div_scale_f32 v131, vcc, 1.0, v128, 1.0
	v_fma_f32 v132, -v129, v130, 1.0
	v_fmac_f32_e32 v130, v132, v130
	v_mul_f32_e32 v132, v131, v130
	v_fma_f32 v133, -v129, v132, v131
	v_fmac_f32_e32 v132, v133, v130
	v_fma_f32 v129, -v129, v132, v131
	v_div_fmas_f32 v129, v129, v130, v132
	v_div_fixup_f32 v184, v129, v128, 1.0
	s_add_u32 s100, s64, 0x160000
	s_addc_u32 s101, s65, 0
	v_pk_mul_f32 v[236:237], v[12:13], v[184:185] op_sel_hi:[1,0]
	v_pk_mul_f32 v[238:239], v[14:15], v[184:185] op_sel_hi:[1,0]
	v_pk_mul_f32 v[240:241], v[8:9], v[184:185] op_sel_hi:[1,0]
	v_pk_mul_f32 v[242:243], v[10:11], v[184:185] op_sel_hi:[1,0]
	v_pk_mul_f32 v[236:237], v[148:149], v[236:237]
	v_pk_mul_f32 v[238:239], v[150:151], v[238:239]
	v_pk_mul_f32 v[240:241], v[152:153], v[240:241]
	v_pk_mul_f32 v[242:243], v[154:155], v[242:243]
	s_nop 0
	global_store_dwordx4 v185, v[236:239], s[100:101] offset:0 nt
	global_store_dwordx4 v185, v[240:243], s[100:101] offset:16 nt
	v_pk_mul_f32 v[244:245], v[4:5], v[184:185] op_sel_hi:[1,0]
	v_pk_mul_f32 v[246:247], v[6:7], v[184:185] op_sel_hi:[1,0]
	v_pk_mul_f32 v[248:249], v[0:1], v[184:185] op_sel_hi:[1,0]
	v_pk_mul_f32 v[250:251], v[2:3], v[184:185] op_sel_hi:[1,0]
	v_pk_mul_f32 v[244:245], v[156:157], v[244:245]
	v_pk_mul_f32 v[246:247], v[158:159], v[246:247]
	v_pk_mul_f32 v[248:249], v[160:161], v[248:249]
	v_pk_mul_f32 v[250:251], v[162:163], v[250:251]
	s_nop 0
	global_store_dwordx4 v185, v[244:247], s[100:101] offset:512 nt
	global_store_dwordx4 v185, v[248:251], s[100:101] offset:528 nt
	s_andn2_b64 vcc, exec, s[22:23]
	s_mov_b64 s[2:3], -1
	s_cbranch_vccnz .LBB0_672
	s_and_b64 vcc, exec, s[0:1]
	s_cbranch_vccnz .LBB0_671
	s_barrier
	s_branch .LBB0_671
